# merge: gate-fragment loads hoisted into last K iteration of each branch (under the final MFMA block)
# speedup vs baseline: 1.0025x; 1.0025x over previous
; DI float lo16(unsigned u) { return __uint_as_float(u << 16); }
; DI float hi16(unsigned u) { return __uint_as_float(u & 0xffff0000u); }
; DI void merge_phase(const P& p, int l, int rows, unsigned char* lds) {
;     ...
;       size_t fb = ((((size_t)tm_ * 8 + tn_) * 8 + w) * 16) * 64 + lane;
;       asm volatile("" : "+v"(fb));
;       const u16* gf = (const u16*)(p.ws + O_GF) + (size_t)br * TA * 1024;
; #pragma unroll
;       for (int mt = 0; mt < 2; ++mt)
; #pragma unroll
;         for (int nt = 0; nt < 2; ++nt)
; #pragma unroll
;           for (int g4 = 0; g4 < 4; ++g4) {
;             uint2 gv = *(const uint2*)(gf + (fb + (size_t)(((mt * 2 + nt) * 4 + g4) * 64)) * 4);
;             tot[mt][nt][4 * g4] += lo16(gv.x) * acc[mt][nt][4 * g4];
;             tot[mt][nt][4 * g4 + 1] += hi16(gv.x) * acc[mt][nt][4 * g4 + 1];
;             tot[mt][nt][4 * g4 + 2] += lo16(gv.y) * acc[mt][nt][4 * g4 + 2];
;             tot[mt][nt][4 * g4 + 3] += hi16(gv.y) * acc[mt][nt][4 * g4 + 3];
;           }
.LBB0_619:
	s_add_i32 s7, s7, 1
	s_waitcnt vmcnt(15)
	v_lshlrev_b32_e32 v226, 16, v70
	v_and_b32_e32 v227, 0xffff0000, v70
	v_lshlrev_b32_e32 v228, 16, v71
	v_and_b32_e32 v229, 0xffff0000, v71
	v_pk_fma_f32 v[186:187], v[50:51], v[226:227], v[186:187]
	v_pk_fma_f32 v[184:185], v[52:53], v[228:229], v[184:185]
	s_waitcnt vmcnt(14)
	v_lshlrev_b32_e32 v226, 16, v72
	v_and_b32_e32 v227, 0xffff0000, v72
	v_lshlrev_b32_e32 v228, 16, v73
	v_and_b32_e32 v229, 0xffff0000, v73
	v_pk_fma_f32 v[182:183], v[54:55], v[226:227], v[182:183]
	v_pk_fma_f32 v[180:181], v[56:57], v[228:229], v[180:181]
	s_waitcnt vmcnt(13)
	v_lshlrev_b32_e32 v226, 16, v74
	v_and_b32_e32 v227, 0xffff0000, v74
	v_lshlrev_b32_e32 v228, 16, v75
	v_and_b32_e32 v229, 0xffff0000, v75
	v_pk_fma_f32 v[176:177], v[58:59], v[226:227], v[176:177]
	v_pk_fma_f32 v[174:175], v[60:61], v[228:229], v[174:175]
	s_waitcnt vmcnt(12)
	v_lshlrev_b32_e32 v226, 16, v76
	v_and_b32_e32 v227, 0xffff0000, v76
	v_lshlrev_b32_e32 v228, 16, v77
	v_and_b32_e32 v229, 0xffff0000, v77
	v_pk_fma_f32 v[170:171], v[62:63], v[226:227], v[170:171]
	v_pk_fma_f32 v[168:169], v[64:65], v[228:229], v[168:169]
	s_waitcnt vmcnt(11)
	v_lshlrev_b32_e32 v226, 16, v78
	v_and_b32_e32 v227, 0xffff0000, v78
	v_lshlrev_b32_e32 v228, 16, v79
	v_and_b32_e32 v229, 0xffff0000, v79
	v_pk_fma_f32 v[166:167], v[34:35], v[226:227], v[166:167]
	v_pk_fma_f32 v[164:165], v[36:37], v[228:229], v[164:165]
	s_waitcnt vmcnt(10)
	v_lshlrev_b32_e32 v226, 16, v80
	v_and_b32_e32 v227, 0xffff0000, v80
	v_lshlrev_b32_e32 v228, 16, v81
	v_and_b32_e32 v229, 0xffff0000, v81
	v_pk_fma_f32 v[162:163], v[38:39], v[226:227], v[162:163]
	v_pk_fma_f32 v[160:161], v[40:41], v[228:229], v[160:161]
	s_waitcnt vmcnt(9)
	v_lshlrev_b32_e32 v226, 16, v82
	v_and_b32_e32 v227, 0xffff0000, v82
	v_lshlrev_b32_e32 v228, 16, v83
	v_and_b32_e32 v229, 0xffff0000, v83
	v_pk_fma_f32 v[158:159], v[42:43], v[226:227], v[158:159]
	v_pk_fma_f32 v[156:157], v[44:45], v[228:229], v[156:157]
	s_waitcnt vmcnt(8)
	v_lshlrev_b32_e32 v226, 16, v84
	v_and_b32_e32 v227, 0xffff0000, v84
	v_lshlrev_b32_e32 v228, 16, v85
	v_and_b32_e32 v229, 0xffff0000, v85
	v_pk_fma_f32 v[154:155], v[46:47], v[226:227], v[154:155]
	v_pk_fma_f32 v[152:153], v[48:49], v[228:229], v[152:153]
	s_waitcnt vmcnt(7)
	v_lshlrev_b32_e32 v226, 16, v90
	v_and_b32_e32 v227, 0xffff0000, v90
	v_lshlrev_b32_e32 v228, 16, v91
	v_and_b32_e32 v229, 0xffff0000, v91
	v_pk_fma_f32 v[150:151], v[18:19], v[226:227], v[150:151]
	v_pk_fma_f32 v[148:149], v[20:21], v[228:229], v[148:149]
	s_waitcnt vmcnt(6)
	v_lshlrev_b32_e32 v226, 16, v92
	v_and_b32_e32 v227, 0xffff0000, v92
	v_lshlrev_b32_e32 v228, 16, v93
	v_and_b32_e32 v229, 0xffff0000, v93
	v_pk_fma_f32 v[146:147], v[22:23], v[226:227], v[146:147]
	v_pk_fma_f32 v[144:145], v[24:25], v[228:229], v[144:145]
	s_waitcnt vmcnt(5)
	v_lshlrev_b32_e32 v226, 16, v94
	v_and_b32_e32 v227, 0xffff0000, v94
	v_lshlrev_b32_e32 v228, 16, v95
	v_and_b32_e32 v229, 0xffff0000, v95
	v_pk_fma_f32 v[142:143], v[26:27], v[226:227], v[142:143]
	v_pk_fma_f32 v[140:141], v[28:29], v[228:229], v[140:141]
	s_waitcnt vmcnt(4)
	v_lshlrev_b32_e32 v226, 16, v96
	v_and_b32_e32 v227, 0xffff0000, v96
	v_lshlrev_b32_e32 v228, 16, v97
	v_and_b32_e32 v229, 0xffff0000, v97
	v_pk_fma_f32 v[138:139], v[30:31], v[226:227], v[138:139]
	v_pk_fma_f32 v[136:137], v[32:33], v[228:229], v[136:137]
	s_waitcnt vmcnt(3)
	v_lshlrev_b32_e32 v226, 16, v98
	v_and_b32_e32 v227, 0xffff0000, v98
	v_lshlrev_b32_e32 v228, 16, v99
	v_and_b32_e32 v229, 0xffff0000, v99
	v_pk_fma_f32 v[134:135], v[2:3], v[226:227], v[134:135]
	v_pk_fma_f32 v[132:133], v[4:5], v[228:229], v[132:133]
	s_waitcnt vmcnt(2)
	v_lshlrev_b32_e32 v226, 16, v100
	v_and_b32_e32 v227, 0xffff0000, v100
	v_lshlrev_b32_e32 v228, 16, v101
	v_and_b32_e32 v229, 0xffff0000, v101
	v_pk_fma_f32 v[130:131], v[6:7], v[226:227], v[130:131]
	v_pk_fma_f32 v[128:129], v[8:9], v[228:229], v[128:129]
	s_waitcnt vmcnt(1)
	v_lshlrev_b32_e32 v226, 16, v102
	v_and_b32_e32 v227, 0xffff0000, v102
	v_lshlrev_b32_e32 v228, 16, v103
	v_and_b32_e32 v229, 0xffff0000, v103
	v_pk_fma_f32 v[126:127], v[10:11], v[226:227], v[126:127]
	v_pk_fma_f32 v[124:125], v[12:13], v[228:229], v[124:125]
	s_waitcnt vmcnt(0)
	v_lshlrev_b32_e32 v226, 16, v104
	v_and_b32_e32 v227, 0xffff0000, v104
	v_lshlrev_b32_e32 v228, 16, v105
	v_and_b32_e32 v229, 0xffff0000, v105
	v_pk_fma_f32 v[122:123], v[14:15], v[226:227], v[122:123]
	v_pk_fma_f32 v[120:121], v[16:17], v[228:229], v[120:121]
	s_cmp_lg_u32 s7, 3
	s_cbranch_scc0 .LBB0_613

; DI void merge_phase(const P& p, int l, int rows, unsigned char* lds) {
;     ...
;       size_t fb = ((((size_t)tm_ * 8 + tn_) * 8 + w) * 16) * 64 + lane;
;       asm volatile("" : "+v"(fb));
;       const u16* gf = (const u16*)(p.ws + O_GF) + (size_t)br * TA * 1024;
; #pragma unroll
;       for (int mt = 0; mt < 2; ++mt)
; #pragma unroll
;         for (int nt = 0; nt < 2; ++nt)
; #pragma unroll
;           for (int g4 = 0; g4 < 4; ++g4) {
;             uint2 gv = *(const uint2*)(gf + (fb + (size_t)(((mt * 2 + nt) * 4 + g4) * 64)) * 4);
.Lmg_gatepf:
	s_cmp_ge_u32 s10, s9
	s_cbranch_scc0 .LBB0_626
	s_mul_i32 s54, s7, 0x4200000
	v_mov_b32_e32 v68, s95
	v_mov_b32_e32 v69, s33
	v_lshl_add_u64 v[68:69], v[68:69], 0, s[54:55]
	v_lshl_add_u64 v[66:67], v[172:173], 3, v[68:69]
	s_nop 0
	v_add_co_u32_e32 v68, vcc, s46, v66
	global_load_dwordx2 v[70:71], v[66:67], off
	global_load_dwordx2 v[72:73], v[66:67], off offset:512
	v_addc_co_u32_e32 v69, vcc, 0, v67, vcc
	global_load_dwordx2 v[74:75], v[66:67], off offset:1024
	global_load_dwordx2 v[76:77], v[66:67], off offset:1536
	global_load_dwordx2 v[78:79], v[66:67], off offset:2048
	global_load_dwordx2 v[80:81], v[66:67], off offset:2560
	global_load_dwordx2 v[82:83], v[66:67], off offset:3072
	global_load_dwordx2 v[84:85], v[66:67], off offset:3584
	global_load_dwordx2 v[90:91], v[68:69], off
	global_load_dwordx2 v[92:93], v[68:69], off offset:512
	global_load_dwordx2 v[94:95], v[68:69], off offset:1024
	global_load_dwordx2 v[96:97], v[68:69], off offset:1536
	global_load_dwordx2 v[98:99], v[68:69], off offset:2048
	global_load_dwordx2 v[100:101], v[68:69], off offset:2560
	global_load_dwordx2 v[102:103], v[68:69], off offset:3072
	global_load_dwordx2 v[104:105], v[68:69], off offset:3584
	s_branch .LBB0_626
